# v55 + attention softmax phase: the five K/V staging global loads issued inside the exp stream instead of as a block before it
# baseline (speedup 1.0000x reference)
; __device__ __forceinline__ void partialSM(f32x16& p0, f32x16& p1, float& m_reg, float& mn, float& alpha) {
;   constexpr float C = SCALE * 1.4426950408889634f;
;   float pmax = p0[0]; for (int r = 1; r < 16; ++r) pmax = fmaxf(pmax, p0[r]); for (int r = 0; r < 16; ++r) pmax = fmaxf(pmax, p1[r]);
;   { auto rr = __builtin_amdgcn_permlane32_swap(__float_as_uint(pmax), __float_as_uint(pmax), false, false);
;     pmax = fmaxf(__uint_as_float(rr[0]), __uint_as_float(rr[1])); }
;   if (__builtin_expect(__all(pmax - m_reg <= THR / SCALE), 1)) { mn = m_reg; alpha = 1.f; }
;   else { mn = fmaxf(m_reg, pmax); alpha = __builtin_amdgcn_exp2f((m_reg - mn) * C); m_reg = mn; }
;   float mnC = -mn * C;
;   for (int r = 0; r < 16; ++r) p0[r] = fmaf(p0[r], C, mnC); for (int r = 0; r < 16; ++r) p1[r] = fmaf(p1[r], C, mnC);
;   for (int r = 0; r < 16; ++r) p0[r] = __builtin_amdgcn_exp2f(p0[r]);
; }
; __device__ __forceinline__ void finishSM(f32x16& p0, f32x16& p1, float alpha, float& l_reg, bf16x8& pa0, bf16x8& pa1, bf16x8& pa2, bf16x8& pa3) {
;   for (int r = 0; r < 16; ++r) p1[r] = __builtin_amdgcn_exp2f(p1[r]);
;   float ps = 0; for (int r = 0; r < 16; ++r) ps += p0[r]; for (int r = 0; r < 16; ++r) ps += p1[r];
;   { auto rr = __builtin_amdgcn_permlane32_swap(__float_as_uint(ps), __float_as_uint(ps), false, false);
;     ps = __uint_as_float(rr[0]) + __uint_as_float(rr[1]); }
;   l_reg = l_reg * alpha + ps;
;     ...
;   PK4(p0, 0, pa0); PK4(p0, 8, pa1); PK4(p1, 0, pa2); PK4(p1, 8, pa3);
;     ...
; }
; __device__ __forceinline__ void qkt(f32x16& p0, f32x16& p1, const char* Kn, const char* Kp, const bf16x8* qr, int r32, int hi) {
;   p0 = f32x16{}; p1 = f32x16{};
; #pragma unroll
;   for (int d0 = 0; d0 < 8; ++d0) { int cb = (d0 * 16 + hi * 8) * 2;
;     bf16x8 b0 = *reinterpret_cast<const bf16x8*>(Kn + KSWZ(r32, cb));
;     bf16x8 b1 = *reinterpret_cast<const bf16x8*>(Kn + KSWZ(32 + r32, cb));
;     p0 = __builtin_amdgcn_mfma_f32_32x32x16_bf16(b0, qr[d0], p0, 0, 0, 0);
;     p1 = __builtin_amdgcn_mfma_f32_32x32x16_bf16(b1, qr[d0], p1, 0, 0, 0); }
; #pragma unroll
;   for (int d1 = 0; d1 < 4; ++d1) { int cb = (d1 * 16 + hi * 8) * 2;
;     bf16x8 b0 = *reinterpret_cast<const bf16x8*>(Kp + KPSWZ(r32, cb));
;     bf16x8 b1 = *reinterpret_cast<const bf16x8*>(Kp + KPSWZ(32 + r32, cb));
;     p0 = __builtin_amdgcn_mfma_f32_32x32x16_bf16(b0, qr[8 + d1], p0, 0, 0, 0);
.Lpp_loop:
	s_barrier
	ds_read_b128 v[192:195], v160 offset:16384
	ds_read_b128 v[196:199], v160 offset:24576
	ds_read_b128 v[200:203], v161 offset:16384
	ds_read_b128 v[204:207], v161 offset:24576
	ds_read_b128 v[208:211], v162 offset:16384
	ds_read_b128 v[212:215], v162 offset:24576
	ds_read_b128 v[216:219], v163 offset:16384
	ds_read_b128 v[220:223], v163 offset:24576
	v_max3_f32 v250, v80, v81, v82
	v_max3_f32 v251, v83, v84, v85
	v_max3_f32 v250, v250, v86, v87
	v_max3_f32 v251, v251, v88, v89
	v_max3_f32 v250, v250, v90, v91
	v_max3_f32 v251, v251, v92, v93
	v_max3_f32 v250, v250, v94, v95
	v_max3_f32 v251, v251, v64, v65
	v_max3_f32 v250, v250, v66, v67
	v_max3_f32 v251, v251, v68, v69
	v_max3_f32 v250, v250, v70, v71
	v_max3_f32 v251, v251, v72, v73
	v_max3_f32 v250, v250, v74, v75
	v_max3_f32 v251, v251, v76, v77
	v_max3_f32 v250, v250, v78, v79
	v_max_f32_e32 v250, v250, v251
	v_cmp_lt_f32_e64 vcc, s64, |v250|
	s_waitcnt vmcnt(0)
	ds_write_b128 v246, v[232:235]
	ds_write_b128 v246, v[236:239] offset:8192
	ds_write_b128 v248, v[240:243]
	ds_write_b128 v244, v[224:227]
	ds_write_b128 v244, v[228:231] offset:8192
	s_cmp_lg_u32 s62, 0
	s_cbranch_scc1 .Lpp_safe_Ba
	s_cbranch_vccnz .Lpp_sw_Ba
	v_exp_f32_e32 v80, v80
	v_exp_f32_e32 v81, v81
	global_load_dwordx4 v[232:235], v180, s[50:51]
	v_exp_f32_e32 v82, v82
	v_exp_f32_e32 v83, v83
	v_exp_f32_e32 v84, v84
	v_exp_f32_e32 v85, v85
	v_exp_f32_e32 v86, v86
	v_exp_f32_e32 v87, v87
	global_load_dwordx4 v[236:239], v180, s[52:53]
	v_exp_f32_e32 v88, v88
	v_exp_f32_e32 v89, v89
	v_exp_f32_e32 v90, v90
	v_exp_f32_e32 v91, v91
	v_exp_f32_e32 v92, v92
	v_exp_f32_e32 v93, v93
	global_load_dwordx4 v[224:227], v180, s[54:55] offset:256
	v_exp_f32_e32 v94, v94
	v_exp_f32_e32 v95, v95
	v_exp_f32_e32 v64, v64
	v_exp_f32_e32 v65, v65
	v_exp_f32_e32 v66, v66
	v_exp_f32_e32 v67, v67
	global_load_dwordx4 v[228:231], v180, s[56:57] offset:256
	v_exp_f32_e32 v68, v68
	v_exp_f32_e32 v69, v69
	v_exp_f32_e32 v70, v70
	v_exp_f32_e32 v71, v71
	v_exp_f32_e32 v72, v72
	v_exp_f32_e32 v73, v73
	global_load_dwordx4 v[240:243], v181, s[58:59]
	v_exp_f32_e32 v74, v74
	v_exp_f32_e32 v75, v75
	v_exp_f32_e32 v76, v76
	v_exp_f32_e32 v77, v77
	v_exp_f32_e32 v78, v78
	v_exp_f32_e32 v79, v79
	v_add_f32_e32 v249, v80, v81
	v_add_f32_e32 v250, v82, v83
	v_add_f32_e32 v251, v84, v85
	v_add_f32_e32 v182, v86, v87
	v_add_f32_e32 v249, v88, v249
	v_add_f32_e32 v250, v89, v250
	v_add_f32_e32 v251, v90, v251
	v_add_f32_e32 v182, v91, v182
	v_add_f32_e32 v249, v92, v249
	v_add_f32_e32 v250, v93, v250
	v_add_f32_e32 v251, v94, v251
	v_add_f32_e32 v182, v95, v182
	v_add_f32_e32 v249, v64, v249
	v_add_f32_e32 v250, v65, v250
	v_add_f32_e32 v251, v66, v251
	v_add_f32_e32 v182, v67, v182
	v_add_f32_e32 v249, v68, v249
	v_add_f32_e32 v250, v69, v250
	v_add_f32_e32 v251, v70, v251
	v_add_f32_e32 v182, v71, v182
	v_add_f32_e32 v249, v72, v249
	v_add_f32_e32 v250, v73, v250
	v_add_f32_e32 v251, v74, v251
	v_add_f32_e32 v182, v75, v182
	v_add_f32_e32 v249, v76, v249
	v_add_f32_e32 v250, v77, v250
	v_add_f32_e32 v251, v78, v251
	v_add_f32_e32 v182, v79, v182
	v_add_f32_e32 v249, v249, v250
	v_add_f32_e32 v251, v251, v182
	v_add_f32_e32 v249, v249, v251
	v_add_f32_e32 v176, v176, v249
	v_cvt_pk_bf16_f32 v144, v80, v81
	v_cvt_pk_bf16_f32 v145, v82, v83
	v_cvt_pk_bf16_f32 v146, v84, v85
	v_cvt_pk_bf16_f32 v147, v86, v87
	v_cvt_pk_bf16_f32 v148, v88, v89
	v_cvt_pk_bf16_f32 v149, v90, v91
	v_cvt_pk_bf16_f32 v150, v92, v93
	v_cvt_pk_bf16_f32 v151, v94, v95
	v_cvt_pk_bf16_f32 v152, v64, v65
	v_cvt_pk_bf16_f32 v153, v66, v67
	v_cvt_pk_bf16_f32 v154, v68, v69
	v_cvt_pk_bf16_f32 v155, v70, v71
	v_cvt_pk_bf16_f32 v156, v72, v73
	v_cvt_pk_bf16_f32 v157, v74, v75
	v_cvt_pk_bf16_f32 v158, v76, v77
	v_cvt_pk_bf16_f32 v159, v78, v79
.Lpp_send_Ba:
	s_add_i32 s11, s11, 1
	s_waitcnt lgkmcnt(6)
	v_mfma_f32_32x32x16_bf16 v[80:95], v[192:195], v[136:139], 0
	v_mfma_f32_32x32x16_bf16 v[64:79], v[196:199], v[136:139], 0
	s_add_i32 s36, s35, 2
	s_min_u32 s36, s36, 67
	s_lshl_b32 s44, s36, 6
	ds_read_b128 v[192:195], v164 offset:16384
	ds_read_b128 v[196:199], v164 offset:24576
	s_waitcnt lgkmcnt(6)
	v_mfma_f32_32x32x16_bf16 v[80:95], v[200:203], v[132:135], v[80:95]
	v_mfma_f32_32x32x16_bf16 v[64:79], v[204:207], v[132:135], v[64:79]
	s_add_i32 s45, s31, s44
	s_add_i32 s46, s24, s44
	s_add_i32 s46, s46, 0xffffff00
	ds_read_b128 v[200:203], v165 offset:16384
	ds_read_b128 v[204:207], v165 offset:24576
	s_waitcnt lgkmcnt(6)
	v_mfma_f32_32x32x16_bf16 v[80:95], v[208:211], v[128:131], v[80:95]
	v_mfma_f32_32x32x16_bf16 v[64:79], v[212:215], v[128:131], v[64:79]
	s_cmp_lt_u32 s36, 4
	s_cselect_b32 s36, s45, s46
	s_add_i32 s37, s35, 1
	ds_read_b128 v[208:211], v166 offset:16384
	ds_read_b128 v[212:215], v166 offset:24576
	s_waitcnt lgkmcnt(6)
	v_mfma_f32_32x32x16_bf16 v[80:95], v[216:219], v[124:127], v[80:95]
	v_mfma_f32_32x32x16_bf16 v[64:79], v[220:223], v[124:127], v[64:79]
	s_min_u32 s37, s37, 67
	s_lshl_b32 s44, s37, 6
	s_add_i32 s45, s31, s44
	ds_read_b128 v[216:219], v167 offset:16384
	ds_read_b128 v[220:223], v167 offset:24576
	s_waitcnt lgkmcnt(6)
	v_mfma_f32_32x32x16_bf16 v[80:95], v[192:195], v[120:123], v[80:95]
	v_mfma_f32_32x32x16_bf16 v[64:79], v[196:199], v[120:123], v[64:79]
	s_add_i32 s46, s24, s44
	s_add_i32 s46, s46, 0xffffff00
	s_cmp_lt_u32 s37, 4
	ds_read_b128 v[192:195], v168 offset:8192
	ds_read_b128 v[196:199], v168 offset:12288
	s_waitcnt lgkmcnt(6)
	v_mfma_f32_32x32x16_bf16 v[80:95], v[200:203], v[140:143], v[80:95]
	v_mfma_f32_32x32x16_bf16 v[64:79], v[204:207], v[140:143], v[64:79]
	s_cselect_b32 s37, s45, s46
	s_add_i32 s35, s35, 1
	s_lshl_b32 s44, s36, 12
	ds_read_b128 v[200:203], v169 offset:8192
	ds_read_b128 v[204:207], v169 offset:12288
	s_waitcnt lgkmcnt(6)
; __device__ __forceinline__ void qkt(f32x16& p0, f32x16& p1, const char* Kn, const char* Kp, const bf16x8* qr, int r32, int hi) {
;   p0 = f32x16{}; p1 = f32x16{};
; #pragma unroll
;   for (int d0 = 0; d0 < 8; ++d0) { int cb = (d0 * 16 + hi * 8) * 2;
;     bf16x8 b0 = *reinterpret_cast<const bf16x8*>(Kn + KSWZ(r32, cb));
;     bf16x8 b1 = *reinterpret_cast<const bf16x8*>(Kn + KSWZ(32 + r32, cb));
;     p0 = __builtin_amdgcn_mfma_f32_32x32x16_bf16(b0, qr[d0], p0, 0, 0, 0);
;     p1 = __builtin_amdgcn_mfma_f32_32x32x16_bf16(b1, qr[d0], p1, 0, 0, 0); }
; #pragma unroll
;   for (int d1 = 0; d1 < 4; ++d1) { int cb = (d1 * 16 + hi * 8) * 2;
;     bf16x8 b0 = *reinterpret_cast<const bf16x8*>(Kp + KPSWZ(r32, cb));
;     bf16x8 b1 = *reinterpret_cast<const bf16x8*>(Kp + KPSWZ(32 + r32, cb));
;     p0 = __builtin_amdgcn_mfma_f32_32x32x16_bf16(b0, qr[8 + d1], p0, 0, 0, 0);
;     p1 = __builtin_amdgcn_mfma_f32_32x32x16_bf16(b1, qr[8 + d1], p1, 0, 0, 0); }
; }
; __device__ __forceinline__ int v_st(int k, int c) { const int kk = (k & ~0xC) | ((k & 4) << 1) | ((k & 8) >> 1); return ((kk >> 3) * 4 + (c >> 5)) * 512 + ((kk & 7) * 32 + (c & 31)) * 2; }
; __device__ __forceinline__ int v_rd_base(int lane) { return ((lane & 3) << 3) | (((lane >> 2) & 3) << 6) | (((lane >> 4) & 1) << 5) | (((lane >> 5) & 1) << 8); }
; template <int OFF> __device__ __forceinline__ s16x4 tr_read(int vb) {
;   s16x4 r; asm volatile("ds_read_b64_tr_b16 %0, %1 offset:%2" : "=&v"(r) : "v"(vb), "i"(OFF) : "memory"); return r;
; }
; template <int D0> __device__ __forceinline__ void pv_one(f32x16& od, int vb, bf16x8 pa0, bf16x8 pa1, bf16x8 pa2, bf16x8 pa3) {
;   const s16x4 l0 = tr_read<v_rd_off(D0, 0, 0)>(vb), h0 = tr_read<v_rd_off(D0, 0, 1)>(vb), l1 = tr_read<v_rd_off(D0, 1, 0)>(vb), h1 = tr_read<v_rd_off(D0, 1, 1)>(vb);
;   const s16x4 l2 = tr_read<v_rd_off(D0, 2, 0)>(vb), h2 = tr_read<v_rd_off(D0, 2, 1)>(vb), l3 = tr_read<v_rd_off(D0, 3, 0)>(vb), h3 = tr_read<v_rd_off(D0, 3, 1)>(vb);
;   asm volatile("s_waitcnt lgkmcnt(0)" ::: "memory"); SBAR();
;     ...
;   od = __builtin_amdgcn_mfma_f32_32x32x16_bf16(pa0, PK(l0, h0), od, 0, 0, 0);
;   od = __builtin_amdgcn_mfma_f32_32x32x16_bf16(pa1, PK(l1, h1), od, 0, 0, 0);
;   od = __builtin_amdgcn_mfma_f32_32x32x16_bf16(pa2, PK(l2, h2), od, 0, 0, 0);
;   od = __builtin_amdgcn_mfma_f32_32x32x16_bf16(pa3, PK(l3, h3), od, 0, 0, 0);
;     ...
; }
	v_mfma_f32_32x32x16_bf16 v[80:95], v[208:211], v[116:119], v[80:95]
	v_mfma_f32_32x32x16_bf16 v[64:79], v[212:215], v[116:119], v[64:79]
	s_add_u32 s50, s47, s44
	s_addc_u32 s51, s63, 0
	s_add_u32 s52, s50, 0x20000
	ds_read_b128 v[208:211], v170 offset:8192
	ds_read_b128 v[212:215], v170 offset:12288
	s_waitcnt lgkmcnt(6)
	v_mfma_f32_32x32x16_bf16 v[80:95], v[216:219], v[112:115], v[80:95]
	v_mfma_f32_32x32x16_bf16 v[64:79], v[220:223], v[112:115], v[64:79]
	s_addc_u32 s53, s51, 0
	s_lshl_b32 s44, s37, 12
	s_add_u32 s54, s47, s44
	ds_read_b128 v[216:219], v171 offset:8192
	ds_read_b128 v[220:223], v171 offset:12288
	s_waitcnt lgkmcnt(6)
	v_mfma_f32_32x32x16_bf16 v[80:95], v[192:195], v[108:111], v[80:95]
	v_mfma_f32_32x32x16_bf16 v[64:79], v[196:199], v[108:111], v[64:79]
	s_addc_u32 s55, s63, 0
	s_add_u32 s56, s54, 0x20000
	s_addc_u32 s57, s55, 0
	ds_read_b64_tr_b16 v[192:193], v174 offset:0
	ds_read_b64_tr_b16 v[194:195], v174 offset:2048
	ds_read_b64_tr_b16 v[196:197], v174 offset:4096
	ds_read_b64_tr_b16 v[198:199], v174 offset:6144
	s_waitcnt lgkmcnt(8)
	v_mfma_f32_32x32x16_bf16 v[80:95], v[200:203], v[104:107], v[80:95]
	v_mfma_f32_32x32x16_bf16 v[64:79], v[204:207], v[104:107], v[64:79]
	s_lshl_b32 s44, s36, 10
	s_add_u32 s58, s60, s44
	s_addc_u32 s59, s61, 0
	ds_read_b64_tr_b16 v[200:201], v174 offset:8192
	ds_read_b64_tr_b16 v[202:203], v174 offset:10240
	ds_read_b64_tr_b16 v[204:205], v174 offset:12288
	ds_read_b64_tr_b16 v[206:207], v174 offset:14336
	s_waitcnt lgkmcnt(10)
	v_mfma_f32_32x32x16_bf16 v[80:95], v[208:211], v[100:103], v[80:95]
	v_mfma_f32_32x32x16_bf16 v[64:79], v[212:215], v[100:103], v[64:79]
	ds_read_b64_tr_b16 v[208:209], v174 offset:512
	ds_read_b64_tr_b16 v[210:211], v174 offset:2560
	ds_read_b64_tr_b16 v[212:213], v174 offset:4608
	ds_read_b64_tr_b16 v[214:215], v174 offset:6656
	s_waitcnt lgkmcnt(12)
	v_mfma_f32_32x32x16_bf16 v[80:95], v[216:219], v[96:99], v[80:95]
	v_mfma_f32_32x32x16_bf16 v[64:79], v[220:223], v[96:99], v[64:79]
	ds_read_b64_tr_b16 v[216:217], v174 offset:8704
	ds_read_b64_tr_b16 v[218:219], v174 offset:10752
	ds_read_b64_tr_b16 v[220:221], v174 offset:12800
	ds_read_b64_tr_b16 v[222:223], v174 offset:14848
	s_waitcnt lgkmcnt(12)
	v_mfma_f32_32x32x16_bf16 v[0:15], v[144:147], v[192:195], v[0:15]
	ds_read_b64_tr_b16 v[192:193], v174 offset:1024
	ds_read_b64_tr_b16 v[194:195], v174 offset:3072
	v_mfma_f32_32x32x16_bf16 v[0:15], v[148:151], v[196:199], v[0:15]
	ds_read_b64_tr_b16 v[196:197], v174 offset:5120
	ds_read_b64_tr_b16 v[198:199], v174 offset:7168
	s_waitcnt lgkmcnt(12)
	v_mfma_f32_32x32x16_bf16 v[0:15], v[152:155], v[200:203], v[0:15]
	ds_read_b64_tr_b16 v[200:201], v174 offset:9216
	ds_read_b64_tr_b16 v[202:203], v174 offset:11264
	v_mfma_f32_32x32x16_bf16 v[0:15], v[156:159], v[204:207], v[0:15]
	ds_read_b64_tr_b16 v[204:205], v174 offset:13312
	ds_read_b64_tr_b16 v[206:207], v174 offset:15360
	s_waitcnt lgkmcnt(12)
	v_mfma_f32_32x32x16_bf16 v[48:63], v[144:147], v[208:211], v[48:63]
	ds_read_b64_tr_b16 v[208:209], v174 offset:1536
	ds_read_b64_tr_b16 v[210:211], v174 offset:3584
	v_mfma_f32_32x32x16_bf16 v[48:63], v[148:151], v[212:215], v[48:63]
	ds_read_b64_tr_b16 v[212:213], v174 offset:5632
	ds_read_b64_tr_b16 v[214:215], v174 offset:7680
	s_waitcnt lgkmcnt(12)
	v_mfma_f32_32x32x16_bf16 v[48:63], v[152:155], v[216:219], v[48:63]
	ds_read_b64_tr_b16 v[216:217], v174 offset:9728
	ds_read_b64_tr_b16 v[218:219], v174 offset:11776
	v_mfma_f32_32x32x16_bf16 v[48:63], v[156:159], v[220:223], v[48:63]
	ds_read_b64_tr_b16 v[220:221], v174 offset:13824
	ds_read_b64_tr_b16 v[222:223], v174 offset:15872
	s_waitcnt lgkmcnt(12)
	v_mfma_f32_32x32x16_bf16 v[32:47], v[144:147], v[192:195], v[32:47]
	v_mfma_f32_32x32x16_bf16 v[32:47], v[148:151], v[196:199], v[32:47]
	s_waitcnt lgkmcnt(8)
	v_mfma_f32_32x32x16_bf16 v[32:47], v[152:155], v[200:203], v[32:47]
	v_mfma_f32_32x32x16_bf16 v[32:47], v[156:159], v[204:207], v[32:47]
	s_waitcnt lgkmcnt(4)
	v_mfma_f32_32x32x16_bf16 v[16:31], v[144:147], v[208:211], v[16:31]
	v_mfma_f32_32x32x16_bf16 v[16:31], v[148:151], v[212:215], v[16:31]
	s_waitcnt lgkmcnt(0)
	v_mfma_f32_32x32x16_bf16 v[16:31], v[152:155], v[216:219], v[16:31]
	v_mfma_f32_32x32x16_bf16 v[16:31], v[156:159], v[220:223], v[16:31]
	s_barrier
; __device__ __forceinline__ void partialSM(f32x16& p0, f32x16& p1, float& m_reg, float& mn, float& alpha) {
;   constexpr float C = SCALE * 1.4426950408889634f;
;   float pmax = p0[0]; for (int r = 1; r < 16; ++r) pmax = fmaxf(pmax, p0[r]); for (int r = 0; r < 16; ++r) pmax = fmaxf(pmax, p1[r]);
;   { auto rr = __builtin_amdgcn_permlane32_swap(__float_as_uint(pmax), __float_as_uint(pmax), false, false);
;     pmax = fmaxf(__uint_as_float(rr[0]), __uint_as_float(rr[1])); }
;   if (__builtin_expect(__all(pmax - m_reg <= THR / SCALE), 1)) { mn = m_reg; alpha = 1.f; }
;   else { mn = fmaxf(m_reg, pmax); alpha = __builtin_amdgcn_exp2f((m_reg - mn) * C); m_reg = mn; }
;   float mnC = -mn * C;
;   for (int r = 0; r < 16; ++r) p0[r] = fmaf(p0[r], C, mnC); for (int r = 0; r < 16; ++r) p1[r] = fmaf(p1[r], C, mnC);
;   for (int r = 0; r < 16; ++r) p0[r] = __builtin_amdgcn_exp2f(p0[r]);
; }
; __device__ __forceinline__ void finishSM(f32x16& p0, f32x16& p1, float alpha, float& l_reg, bf16x8& pa0, bf16x8& pa1, bf16x8& pa2, bf16x8& pa3) {
;   for (int r = 0; r < 16; ++r) p1[r] = __builtin_amdgcn_exp2f(p1[r]);
;   float ps = 0; for (int r = 0; r < 16; ++r) ps += p0[r]; for (int r = 0; r < 16; ++r) ps += p1[r];
;   { auto rr = __builtin_amdgcn_permlane32_swap(__float_as_uint(ps), __float_as_uint(ps), false, false);
;     ps = __uint_as_float(rr[0]) + __uint_as_float(rr[1]); }
;   l_reg = l_reg * alpha + ps;
;     ...
;   PK4(p0, 0, pa0); PK4(p0, 8, pa1); PK4(p1, 0, pa2); PK4(p1, 8, pa3);
;     ...
; }
	ds_read_b128 v[192:195], v160
	ds_read_b128 v[196:199], v160 offset:8192
	ds_read_b128 v[200:203], v161
	ds_read_b128 v[204:207], v161 offset:8192
	ds_read_b128 v[208:211], v162
	ds_read_b128 v[212:215], v162 offset:8192
	ds_read_b128 v[216:219], v163
	ds_read_b128 v[220:223], v163 offset:8192
	v_max3_f32 v250, v80, v81, v82
	v_max3_f32 v251, v83, v84, v85
	v_max3_f32 v250, v250, v86, v87
	v_max3_f32 v251, v251, v88, v89
	v_max3_f32 v250, v250, v90, v91
	v_max3_f32 v251, v251, v92, v93
	v_max3_f32 v250, v250, v94, v95
	v_max3_f32 v251, v251, v64, v65
	v_max3_f32 v250, v250, v66, v67
	v_max3_f32 v251, v251, v68, v69
	v_max3_f32 v250, v250, v70, v71
	v_max3_f32 v251, v251, v72, v73
	v_max3_f32 v250, v250, v74, v75
	v_max3_f32 v251, v251, v76, v77
	v_max3_f32 v250, v250, v78, v79
	v_max_f32_e32 v250, v250, v251
	v_cmp_lt_f32_e64 vcc, s64, |v250|
	s_waitcnt vmcnt(0)
	ds_write_b128 v247, v[232:235]
	ds_write_b128 v247, v[236:239] offset:8192
	ds_write_b128 v183, v[240:243]
	ds_write_b128 v245, v[224:227]
	ds_write_b128 v245, v[228:231] offset:8192
	s_cmp_lg_u32 s62, 0
	s_cbranch_scc1 .Lpp_safe_Bb
	s_cbranch_vccnz .Lpp_sw_Bb
	v_exp_f32_e32 v80, v80
	v_exp_f32_e32 v81, v81
	global_load_dwordx4 v[232:235], v180, s[50:51]
	v_exp_f32_e32 v82, v82
	v_exp_f32_e32 v83, v83
	v_exp_f32_e32 v84, v84
	v_exp_f32_e32 v85, v85
	v_exp_f32_e32 v86, v86
	v_exp_f32_e32 v87, v87
	global_load_dwordx4 v[236:239], v180, s[52:53]
	v_exp_f32_e32 v88, v88
	v_exp_f32_e32 v89, v89
	v_exp_f32_e32 v90, v90
	v_exp_f32_e32 v91, v91
	v_exp_f32_e32 v92, v92
	v_exp_f32_e32 v93, v93
	global_load_dwordx4 v[224:227], v180, s[54:55] offset:256
	v_exp_f32_e32 v94, v94
	v_exp_f32_e32 v95, v95
	v_exp_f32_e32 v64, v64
	v_exp_f32_e32 v65, v65
	v_exp_f32_e32 v66, v66
	v_exp_f32_e32 v67, v67
	global_load_dwordx4 v[228:231], v180, s[56:57] offset:256
	v_exp_f32_e32 v68, v68
	v_exp_f32_e32 v69, v69
	v_exp_f32_e32 v70, v70
	v_exp_f32_e32 v71, v71
	v_exp_f32_e32 v72, v72
	v_exp_f32_e32 v73, v73
	global_load_dwordx4 v[240:243], v181, s[58:59]
	v_exp_f32_e32 v74, v74
	v_exp_f32_e32 v75, v75
	v_exp_f32_e32 v76, v76
	v_exp_f32_e32 v77, v77
	v_exp_f32_e32 v78, v78
	v_exp_f32_e32 v79, v79
	v_add_f32_e32 v249, v80, v81
	v_add_f32_e32 v250, v82, v83
	v_add_f32_e32 v251, v84, v85
	v_add_f32_e32 v182, v86, v87
	v_add_f32_e32 v249, v88, v249
	v_add_f32_e32 v250, v89, v250
	v_add_f32_e32 v251, v90, v251
	v_add_f32_e32 v182, v91, v182
	v_add_f32_e32 v249, v92, v249
	v_add_f32_e32 v250, v93, v250
	v_add_f32_e32 v251, v94, v251
	v_add_f32_e32 v182, v95, v182
	v_add_f32_e32 v249, v64, v249
	v_add_f32_e32 v250, v65, v250
	v_add_f32_e32 v251, v66, v251
	v_add_f32_e32 v182, v67, v182
	v_add_f32_e32 v249, v68, v249
	v_add_f32_e32 v250, v69, v250
	v_add_f32_e32 v251, v70, v251
	v_add_f32_e32 v182, v71, v182
	v_add_f32_e32 v249, v72, v249
	v_add_f32_e32 v250, v73, v250
	v_add_f32_e32 v251, v74, v251
	v_add_f32_e32 v182, v75, v182
	v_add_f32_e32 v249, v76, v249
	v_add_f32_e32 v250, v77, v250
	v_add_f32_e32 v251, v78, v251
	v_add_f32_e32 v182, v79, v182
	v_add_f32_e32 v249, v249, v250
	v_add_f32_e32 v251, v251, v182
	v_add_f32_e32 v249, v249, v251
	v_add_f32_e32 v176, v176, v249
	v_cvt_pk_bf16_f32 v144, v80, v81
	v_cvt_pk_bf16_f32 v145, v82, v83
	v_cvt_pk_bf16_f32 v146, v84, v85
	v_cvt_pk_bf16_f32 v147, v86, v87
	v_cvt_pk_bf16_f32 v148, v88, v89
	v_cvt_pk_bf16_f32 v149, v90, v91
	v_cvt_pk_bf16_f32 v150, v92, v93
	v_cvt_pk_bf16_f32 v151, v94, v95
	v_cvt_pk_bf16_f32 v152, v64, v65
	v_cvt_pk_bf16_f32 v153, v66, v67
	v_cvt_pk_bf16_f32 v154, v68, v69
	v_cvt_pk_bf16_f32 v155, v70, v71
	v_cvt_pk_bf16_f32 v156, v72, v73
	v_cvt_pk_bf16_f32 v157, v74, v75
	v_cvt_pk_bf16_f32 v158, v76, v77
	v_cvt_pk_bf16_f32 v159, v78, v79

; __device__ __forceinline__ void partialSM(f32x16& p0, f32x16& p1, float& m_reg, float& mn, float& alpha) {
;   constexpr float C = SCALE * 1.4426950408889634f;
;   float pmax = p0[0]; for (int r = 1; r < 16; ++r) pmax = fmaxf(pmax, p0[r]); for (int r = 0; r < 16; ++r) pmax = fmaxf(pmax, p1[r]);
;   { auto rr = __builtin_amdgcn_permlane32_swap(__float_as_uint(pmax), __float_as_uint(pmax), false, false);
;     pmax = fmaxf(__uint_as_float(rr[0]), __uint_as_float(rr[1])); }
;   if (__builtin_expect(__all(pmax - m_reg <= THR / SCALE), 1)) { mn = m_reg; alpha = 1.f; }
;   else { mn = fmaxf(m_reg, pmax); alpha = __builtin_amdgcn_exp2f((m_reg - mn) * C); m_reg = mn; }
;   float mnC = -mn * C;
;   for (int r = 0; r < 16; ++r) p0[r] = fmaf(p0[r], C, mnC); for (int r = 0; r < 16; ++r) p1[r] = fmaf(p1[r], C, mnC);
;   for (int r = 0; r < 16; ++r) p0[r] = __builtin_amdgcn_exp2f(p0[r]);
; }
; __device__ __forceinline__ void finishSM(f32x16& p0, f32x16& p1, float alpha, float& l_reg, bf16x8& pa0, bf16x8& pa1, bf16x8& pa2, bf16x8& pa3) {
;   for (int r = 0; r < 16; ++r) p1[r] = __builtin_amdgcn_exp2f(p1[r]);
;   float ps = 0; for (int r = 0; r < 16; ++r) ps += p0[r]; for (int r = 0; r < 16; ++r) ps += p1[r];
;   { auto rr = __builtin_amdgcn_permlane32_swap(__float_as_uint(ps), __float_as_uint(ps), false, false);
;     ps = __uint_as_float(rr[0]) + __uint_as_float(rr[1]); }
;   l_reg = l_reg * alpha + ps;
;     ...
;   PK4(p0, 0, pa0); PK4(p0, 8, pa1); PK4(p1, 0, pa2); PK4(p1, 8, pa3);
;     ...
; }
; __device__ __forceinline__ void qkt(f32x16& p0, f32x16& p1, const char* Kn, const char* Kp, const bf16x8* qr, int r32, int hi) {
;   p0 = f32x16{}; p1 = f32x16{};
; #pragma unroll
;   for (int d0 = 0; d0 < 8; ++d0) { int cb = (d0 * 16 + hi * 8) * 2;
;     bf16x8 b0 = *reinterpret_cast<const bf16x8*>(Kn + KSWZ(r32, cb));
;     bf16x8 b1 = *reinterpret_cast<const bf16x8*>(Kn + KSWZ(32 + r32, cb));
;     p0 = __builtin_amdgcn_mfma_f32_32x32x16_bf16(b0, qr[d0], p0, 0, 0, 0);
;     p1 = __builtin_amdgcn_mfma_f32_32x32x16_bf16(b1, qr[d0], p1, 0, 0, 0); }
; #pragma unroll
;   for (int d1 = 0; d1 < 4; ++d1) { int cb = (d1 * 16 + hi * 8) * 2;
;     bf16x8 b0 = *reinterpret_cast<const bf16x8*>(Kp + KPSWZ(r32, cb));
;     bf16x8 b1 = *reinterpret_cast<const bf16x8*>(Kp + KPSWZ(32 + r32, cb));
;     p0 = __builtin_amdgcn_mfma_f32_32x32x16_bf16(b0, qr[8 + d1], p0, 0, 0, 0);
.Lpp_aloop:
	v_max3_f32 v250, v80, v81, v82
	v_max3_f32 v251, v83, v84, v85
	v_max3_f32 v250, v250, v86, v87
	v_max3_f32 v251, v251, v88, v89
	v_max3_f32 v250, v250, v90, v91
	v_max3_f32 v251, v251, v92, v93
	v_max3_f32 v250, v250, v94, v95
	v_max3_f32 v251, v251, v64, v65
	v_max3_f32 v250, v250, v66, v67
	v_max3_f32 v251, v251, v68, v69
	v_max3_f32 v250, v250, v70, v71
	v_max3_f32 v251, v251, v72, v73
	v_max3_f32 v250, v250, v74, v75
	v_max3_f32 v251, v251, v76, v77
	v_max3_f32 v250, v250, v78, v79
	v_max_f32_e32 v250, v250, v251
	v_cmp_lt_f32_e64 vcc, s64, |v250|
	s_waitcnt vmcnt(0)
	ds_write_b128 v246, v[232:235]
	ds_write_b128 v246, v[236:239] offset:8192
	ds_write_b128 v248, v[240:243]
	ds_write_b128 v244, v[224:227]
	ds_write_b128 v244, v[228:231] offset:8192
	s_cmp_lg_u32 s62, 0
	s_cbranch_scc1 .Lpp_safe_Aa
	s_cbranch_vccnz .Lpp_sw_Aa
	v_exp_f32_e32 v80, v80
	v_exp_f32_e32 v81, v81
	global_load_dwordx4 v[232:235], v180, s[50:51]
	v_exp_f32_e32 v82, v82
	v_exp_f32_e32 v83, v83
	v_exp_f32_e32 v84, v84
	v_exp_f32_e32 v85, v85
	v_exp_f32_e32 v86, v86
	v_exp_f32_e32 v87, v87
	global_load_dwordx4 v[236:239], v180, s[52:53]
	v_exp_f32_e32 v88, v88
	v_exp_f32_e32 v89, v89
	v_exp_f32_e32 v90, v90
	v_exp_f32_e32 v91, v91
	v_exp_f32_e32 v92, v92
	v_exp_f32_e32 v93, v93
	global_load_dwordx4 v[224:227], v180, s[54:55] offset:256
	v_exp_f32_e32 v94, v94
	v_exp_f32_e32 v95, v95
	v_exp_f32_e32 v64, v64
	v_exp_f32_e32 v65, v65
	v_exp_f32_e32 v66, v66
	v_exp_f32_e32 v67, v67
	global_load_dwordx4 v[228:231], v180, s[56:57] offset:256
	v_exp_f32_e32 v68, v68
	v_exp_f32_e32 v69, v69
	v_exp_f32_e32 v70, v70
	v_exp_f32_e32 v71, v71
	v_exp_f32_e32 v72, v72
	v_exp_f32_e32 v73, v73
	global_load_dwordx4 v[240:243], v181, s[58:59]
	v_exp_f32_e32 v74, v74
	v_exp_f32_e32 v75, v75
	v_exp_f32_e32 v76, v76
	v_exp_f32_e32 v77, v77
	v_exp_f32_e32 v78, v78
	v_exp_f32_e32 v79, v79
	v_add_f32_e32 v249, v80, v81
	v_add_f32_e32 v250, v82, v83
	v_add_f32_e32 v251, v84, v85
	v_add_f32_e32 v182, v86, v87
	v_add_f32_e32 v249, v88, v249
	v_add_f32_e32 v250, v89, v250
	v_add_f32_e32 v251, v90, v251
	v_add_f32_e32 v182, v91, v182
	v_add_f32_e32 v249, v92, v249
	v_add_f32_e32 v250, v93, v250
	v_add_f32_e32 v251, v94, v251
	v_add_f32_e32 v182, v95, v182
	v_add_f32_e32 v249, v64, v249
	v_add_f32_e32 v250, v65, v250
	v_add_f32_e32 v251, v66, v251
	v_add_f32_e32 v182, v67, v182
	v_add_f32_e32 v249, v68, v249
	v_add_f32_e32 v250, v69, v250
	v_add_f32_e32 v251, v70, v251
	v_add_f32_e32 v182, v71, v182
	v_add_f32_e32 v249, v72, v249
	v_add_f32_e32 v250, v73, v250
	v_add_f32_e32 v251, v74, v251
	v_add_f32_e32 v182, v75, v182
	v_add_f32_e32 v249, v76, v249
	v_add_f32_e32 v250, v77, v250
	v_add_f32_e32 v251, v78, v251
	v_add_f32_e32 v182, v79, v182
	v_add_f32_e32 v249, v249, v250
	v_add_f32_e32 v251, v251, v182
	v_add_f32_e32 v249, v249, v251
	v_add_f32_e32 v176, v176, v249
	v_cvt_pk_bf16_f32 v144, v80, v81
	v_cvt_pk_bf16_f32 v145, v82, v83
	v_cvt_pk_bf16_f32 v146, v84, v85
	v_cvt_pk_bf16_f32 v147, v86, v87
	v_cvt_pk_bf16_f32 v148, v88, v89
	v_cvt_pk_bf16_f32 v149, v90, v91
	v_cvt_pk_bf16_f32 v150, v92, v93
	v_cvt_pk_bf16_f32 v151, v94, v95
	v_cvt_pk_bf16_f32 v152, v64, v65
	v_cvt_pk_bf16_f32 v153, v66, v67
	v_cvt_pk_bf16_f32 v154, v68, v69
	v_cvt_pk_bf16_f32 v155, v70, v71
	v_cvt_pk_bf16_f32 v156, v72, v73
	v_cvt_pk_bf16_f32 v157, v74, v75
	v_cvt_pk_bf16_f32 v158, v76, v77
	v_cvt_pk_bf16_f32 v159, v78, v79
.Lpp_send_Aa:
	s_waitcnt lgkmcnt(0)
	s_barrier
	s_add_i32 s11, s11, 1
	ds_read_b128 v[192:195], v160 offset:16384
	ds_read_b128 v[196:199], v160 offset:24576
	ds_read_b128 v[200:203], v161 offset:16384
	ds_read_b128 v[204:207], v161 offset:24576
	ds_read_b128 v[208:211], v162 offset:16384
	ds_read_b128 v[212:215], v162 offset:24576
	ds_read_b128 v[216:219], v163 offset:16384
	ds_read_b128 v[220:223], v163 offset:24576
	s_waitcnt lgkmcnt(6)
	v_mfma_f32_32x32x16_bf16 v[80:95], v[192:195], v[136:139], 0
	v_mfma_f32_32x32x16_bf16 v[64:79], v[196:199], v[136:139], 0
	s_add_i32 s36, s35, 2
	s_min_u32 s36, s36, 67
	s_lshl_b32 s44, s36, 6
	ds_read_b128 v[192:195], v164 offset:16384
	ds_read_b128 v[196:199], v164 offset:24576
	s_waitcnt lgkmcnt(6)
	v_mfma_f32_32x32x16_bf16 v[80:95], v[200:203], v[132:135], v[80:95]
	v_mfma_f32_32x32x16_bf16 v[64:79], v[204:207], v[132:135], v[64:79]
	s_add_i32 s45, s31, s44
	s_add_i32 s46, s24, s44
	s_add_i32 s46, s46, 0xffffff00
	ds_read_b128 v[200:203], v165 offset:16384
	ds_read_b128 v[204:207], v165 offset:24576
	s_waitcnt lgkmcnt(6)
	v_mfma_f32_32x32x16_bf16 v[80:95], v[208:211], v[128:131], v[80:95]
	v_mfma_f32_32x32x16_bf16 v[64:79], v[212:215], v[128:131], v[64:79]
	s_cmp_lt_u32 s36, 4
	s_cselect_b32 s36, s45, s46
	s_add_i32 s37, s35, 1
	ds_read_b128 v[208:211], v166 offset:16384
	ds_read_b128 v[212:215], v166 offset:24576
	s_waitcnt lgkmcnt(6)
	v_mfma_f32_32x32x16_bf16 v[80:95], v[216:219], v[124:127], v[80:95]
	v_mfma_f32_32x32x16_bf16 v[64:79], v[220:223], v[124:127], v[64:79]
	s_min_u32 s37, s37, 67
	s_lshl_b32 s44, s37, 6
	s_add_i32 s45, s31, s44
	ds_read_b128 v[216:219], v167 offset:16384
	ds_read_b128 v[220:223], v167 offset:24576
	s_waitcnt lgkmcnt(6)
	v_mfma_f32_32x32x16_bf16 v[80:95], v[192:195], v[120:123], v[80:95]
	v_mfma_f32_32x32x16_bf16 v[64:79], v[196:199], v[120:123], v[64:79]
	s_add_i32 s46, s24, s44
	s_add_i32 s46, s46, 0xffffff00
	s_cmp_lt_u32 s37, 4
	ds_read_b128 v[192:195], v168 offset:8192
	ds_read_b128 v[196:199], v168 offset:12288
	s_waitcnt lgkmcnt(6)
	v_mfma_f32_32x32x16_bf16 v[80:95], v[200:203], v[140:143], v[80:95]
	v_mfma_f32_32x32x16_bf16 v[64:79], v[204:207], v[140:143], v[64:79]
	s_cselect_b32 s37, s45, s46
	s_add_i32 s35, s35, 1
	s_lshl_b32 s44, s36, 12
	ds_read_b128 v[200:203], v169 offset:8192
	ds_read_b128 v[204:207], v169 offset:12288
	s_waitcnt lgkmcnt(6)
; __device__ __forceinline__ void qkt(f32x16& p0, f32x16& p1, const char* Kn, const char* Kp, const bf16x8* qr, int r32, int hi) {
;   p0 = f32x16{}; p1 = f32x16{};
; #pragma unroll
;   for (int d0 = 0; d0 < 8; ++d0) { int cb = (d0 * 16 + hi * 8) * 2;
;     bf16x8 b0 = *reinterpret_cast<const bf16x8*>(Kn + KSWZ(r32, cb));
;     bf16x8 b1 = *reinterpret_cast<const bf16x8*>(Kn + KSWZ(32 + r32, cb));
;     p0 = __builtin_amdgcn_mfma_f32_32x32x16_bf16(b0, qr[d0], p0, 0, 0, 0);
;     p1 = __builtin_amdgcn_mfma_f32_32x32x16_bf16(b1, qr[d0], p1, 0, 0, 0); }
; #pragma unroll
;   for (int d1 = 0; d1 < 4; ++d1) { int cb = (d1 * 16 + hi * 8) * 2;
;     bf16x8 b0 = *reinterpret_cast<const bf16x8*>(Kp + KPSWZ(r32, cb));
;     bf16x8 b1 = *reinterpret_cast<const bf16x8*>(Kp + KPSWZ(32 + r32, cb));
;     p0 = __builtin_amdgcn_mfma_f32_32x32x16_bf16(b0, qr[8 + d1], p0, 0, 0, 0);
;     p1 = __builtin_amdgcn_mfma_f32_32x32x16_bf16(b1, qr[8 + d1], p1, 0, 0, 0); }
; }
; __device__ __forceinline__ int v_st(int k, int c) { const int kk = (k & ~0xC) | ((k & 4) << 1) | ((k & 8) >> 1); return ((kk >> 3) * 4 + (c >> 5)) * 512 + ((kk & 7) * 32 + (c & 31)) * 2; }
; __device__ __forceinline__ int v_rd_base(int lane) { return ((lane & 3) << 3) | (((lane >> 2) & 3) << 6) | (((lane >> 4) & 1) << 5) | (((lane >> 5) & 1) << 8); }
; template <int OFF> __device__ __forceinline__ s16x4 tr_read(int vb) {
;   s16x4 r; asm volatile("ds_read_b64_tr_b16 %0, %1 offset:%2" : "=&v"(r) : "v"(vb), "i"(OFF) : "memory"); return r;
; }
; template <int D0> __device__ __forceinline__ void pv_one(f32x16& od, int vb, bf16x8 pa0, bf16x8 pa1, bf16x8 pa2, bf16x8 pa3) {
;   const s16x4 l0 = tr_read<v_rd_off(D0, 0, 0)>(vb), h0 = tr_read<v_rd_off(D0, 0, 1)>(vb), l1 = tr_read<v_rd_off(D0, 1, 0)>(vb), h1 = tr_read<v_rd_off(D0, 1, 1)>(vb);
;   const s16x4 l2 = tr_read<v_rd_off(D0, 2, 0)>(vb), h2 = tr_read<v_rd_off(D0, 2, 1)>(vb), l3 = tr_read<v_rd_off(D0, 3, 0)>(vb), h3 = tr_read<v_rd_off(D0, 3, 1)>(vb);
;   asm volatile("s_waitcnt lgkmcnt(0)" ::: "memory"); SBAR();
;     ...
;   od = __builtin_amdgcn_mfma_f32_32x32x16_bf16(pa0, PK(l0, h0), od, 0, 0, 0);
;   od = __builtin_amdgcn_mfma_f32_32x32x16_bf16(pa1, PK(l1, h1), od, 0, 0, 0);
;   od = __builtin_amdgcn_mfma_f32_32x32x16_bf16(pa2, PK(l2, h2), od, 0, 0, 0);
;   od = __builtin_amdgcn_mfma_f32_32x32x16_bf16(pa3, PK(l3, h3), od, 0, 0, 0);
;     ...
; }
	v_mfma_f32_32x32x16_bf16 v[80:95], v[208:211], v[116:119], v[80:95]
	v_mfma_f32_32x32x16_bf16 v[64:79], v[212:215], v[116:119], v[64:79]
	s_add_u32 s50, s47, s44
	s_addc_u32 s51, s63, 0
	s_add_u32 s52, s50, 0x20000
	ds_read_b128 v[208:211], v170 offset:8192
	ds_read_b128 v[212:215], v170 offset:12288
	s_waitcnt lgkmcnt(6)
	v_mfma_f32_32x32x16_bf16 v[80:95], v[216:219], v[112:115], v[80:95]
	v_mfma_f32_32x32x16_bf16 v[64:79], v[220:223], v[112:115], v[64:79]
	s_addc_u32 s53, s51, 0
	s_lshl_b32 s44, s37, 12
	s_add_u32 s54, s47, s44
	ds_read_b128 v[216:219], v171 offset:8192
	ds_read_b128 v[220:223], v171 offset:12288
	s_waitcnt lgkmcnt(6)
	v_mfma_f32_32x32x16_bf16 v[80:95], v[192:195], v[108:111], v[80:95]
	v_mfma_f32_32x32x16_bf16 v[64:79], v[196:199], v[108:111], v[64:79]
	s_addc_u32 s55, s63, 0
	s_add_u32 s56, s54, 0x20000
	s_addc_u32 s57, s55, 0
	ds_read_b64_tr_b16 v[192:193], v174 offset:0
	ds_read_b64_tr_b16 v[194:195], v174 offset:2048
	ds_read_b64_tr_b16 v[196:197], v174 offset:4096
	ds_read_b64_tr_b16 v[198:199], v174 offset:6144
	s_waitcnt lgkmcnt(8)
	v_mfma_f32_32x32x16_bf16 v[80:95], v[200:203], v[104:107], v[80:95]
	v_mfma_f32_32x32x16_bf16 v[64:79], v[204:207], v[104:107], v[64:79]
	s_lshl_b32 s44, s36, 10
	s_add_u32 s58, s60, s44
	s_addc_u32 s59, s61, 0
	ds_read_b64_tr_b16 v[200:201], v174 offset:8192
	ds_read_b64_tr_b16 v[202:203], v174 offset:10240
	ds_read_b64_tr_b16 v[204:205], v174 offset:12288
	ds_read_b64_tr_b16 v[206:207], v174 offset:14336
	s_waitcnt lgkmcnt(10)
	v_mfma_f32_32x32x16_bf16 v[80:95], v[208:211], v[100:103], v[80:95]
	v_mfma_f32_32x32x16_bf16 v[64:79], v[212:215], v[100:103], v[64:79]
	ds_read_b64_tr_b16 v[208:209], v174 offset:512
	ds_read_b64_tr_b16 v[210:211], v174 offset:2560
	ds_read_b64_tr_b16 v[212:213], v174 offset:4608
	ds_read_b64_tr_b16 v[214:215], v174 offset:6656
	s_waitcnt lgkmcnt(12)
	v_mfma_f32_32x32x16_bf16 v[80:95], v[216:219], v[96:99], v[80:95]
	v_mfma_f32_32x32x16_bf16 v[64:79], v[220:223], v[96:99], v[64:79]
	ds_read_b64_tr_b16 v[216:217], v174 offset:8704
	ds_read_b64_tr_b16 v[218:219], v174 offset:10752
	ds_read_b64_tr_b16 v[220:221], v174 offset:12800
	ds_read_b64_tr_b16 v[222:223], v174 offset:14848
	s_waitcnt lgkmcnt(12)
	v_mfma_f32_32x32x16_bf16 v[0:15], v[144:147], v[192:195], v[0:15]
	ds_read_b64_tr_b16 v[192:193], v174 offset:1024
	ds_read_b64_tr_b16 v[194:195], v174 offset:3072
	v_mfma_f32_32x32x16_bf16 v[0:15], v[148:151], v[196:199], v[0:15]
	ds_read_b64_tr_b16 v[196:197], v174 offset:5120
	ds_read_b64_tr_b16 v[198:199], v174 offset:7168
	s_waitcnt lgkmcnt(12)
	v_mfma_f32_32x32x16_bf16 v[0:15], v[152:155], v[200:203], v[0:15]
	ds_read_b64_tr_b16 v[200:201], v174 offset:9216
	ds_read_b64_tr_b16 v[202:203], v174 offset:11264
	v_mfma_f32_32x32x16_bf16 v[0:15], v[156:159], v[204:207], v[0:15]
	ds_read_b64_tr_b16 v[204:205], v174 offset:13312
	ds_read_b64_tr_b16 v[206:207], v174 offset:15360
	s_waitcnt lgkmcnt(12)
	v_mfma_f32_32x32x16_bf16 v[48:63], v[144:147], v[208:211], v[48:63]
	ds_read_b64_tr_b16 v[208:209], v174 offset:1536
	ds_read_b64_tr_b16 v[210:211], v174 offset:3584
	v_mfma_f32_32x32x16_bf16 v[48:63], v[148:151], v[212:215], v[48:63]
	ds_read_b64_tr_b16 v[212:213], v174 offset:5632
	ds_read_b64_tr_b16 v[214:215], v174 offset:7680
	s_waitcnt lgkmcnt(12)
	v_mfma_f32_32x32x16_bf16 v[48:63], v[152:155], v[216:219], v[48:63]
	ds_read_b64_tr_b16 v[216:217], v174 offset:9728
	ds_read_b64_tr_b16 v[218:219], v174 offset:11776
	v_mfma_f32_32x32x16_bf16 v[48:63], v[156:159], v[220:223], v[48:63]
	ds_read_b64_tr_b16 v[220:221], v174 offset:13824
	ds_read_b64_tr_b16 v[222:223], v174 offset:15872
	s_waitcnt lgkmcnt(12)
	v_mfma_f32_32x32x16_bf16 v[32:47], v[144:147], v[192:195], v[32:47]
	v_mfma_f32_32x32x16_bf16 v[32:47], v[148:151], v[196:199], v[32:47]
	s_waitcnt lgkmcnt(8)
	v_mfma_f32_32x32x16_bf16 v[32:47], v[152:155], v[200:203], v[32:47]
	v_mfma_f32_32x32x16_bf16 v[32:47], v[156:159], v[204:207], v[32:47]
	s_waitcnt lgkmcnt(4)
	v_mfma_f32_32x32x16_bf16 v[16:31], v[144:147], v[208:211], v[16:31]
	v_mfma_f32_32x32x16_bf16 v[16:31], v[148:151], v[212:215], v[16:31]
	s_waitcnt lgkmcnt(0)
	v_mfma_f32_32x32x16_bf16 v[16:31], v[152:155], v[216:219], v[16:31]
	v_mfma_f32_32x32x16_bf16 v[16:31], v[156:159], v[220:223], v[16:31]
	v_max3_f32 v250, v80, v81, v82
	v_max3_f32 v251, v83, v84, v85
	v_max3_f32 v250, v250, v86, v87
	v_max3_f32 v251, v251, v88, v89
	v_max3_f32 v250, v250, v90, v91
	v_max3_f32 v251, v251, v92, v93
	v_max3_f32 v250, v250, v94, v95
	v_max3_f32 v251, v251, v64, v65
	v_max3_f32 v250, v250, v66, v67
	v_max3_f32 v251, v251, v68, v69
	v_max3_f32 v250, v250, v70, v71
	v_max3_f32 v251, v251, v72, v73
	v_max3_f32 v250, v250, v74, v75
	v_max3_f32 v251, v251, v76, v77
	v_max3_f32 v250, v250, v78, v79
	v_max_f32_e32 v250, v250, v251
	v_cmp_lt_f32_e64 vcc, s64, |v250|
	s_waitcnt vmcnt(0)
	ds_write_b128 v247, v[232:235]
	ds_write_b128 v247, v[236:239] offset:8192
	ds_write_b128 v183, v[240:243]
	ds_write_b128 v245, v[224:227]
	ds_write_b128 v245, v[228:231] offset:8192
	s_cmp_lg_u32 s62, 0
	s_cbranch_scc1 .Lpp_safe_Ab
; __device__ __forceinline__ void finishSM(f32x16& p0, f32x16& p1, float alpha, float& l_reg, bf16x8& pa0, bf16x8& pa1, bf16x8& pa2, bf16x8& pa3) {
;   for (int r = 0; r < 16; ++r) p1[r] = __builtin_amdgcn_exp2f(p1[r]);
;   float ps = 0; for (int r = 0; r < 16; ++r) ps += p0[r]; for (int r = 0; r < 16; ++r) ps += p1[r];
;   { auto rr = __builtin_amdgcn_permlane32_swap(__float_as_uint(ps), __float_as_uint(ps), false, false);
;     ps = __uint_as_float(rr[0]) + __uint_as_float(rr[1]); }
;   l_reg = l_reg * alpha + ps;
;     ...
;   PK4(p0, 0, pa0); PK4(p0, 8, pa1); PK4(p1, 0, pa2); PK4(p1, 8, pa3);
;     ...
; }
	s_cbranch_vccnz .Lpp_sw_Ab
	v_exp_f32_e32 v80, v80
	v_exp_f32_e32 v81, v81
	global_load_dwordx4 v[232:235], v180, s[50:51]
	v_exp_f32_e32 v82, v82
	v_exp_f32_e32 v83, v83
	v_exp_f32_e32 v84, v84
	v_exp_f32_e32 v85, v85
	v_exp_f32_e32 v86, v86
	v_exp_f32_e32 v87, v87
	global_load_dwordx4 v[236:239], v180, s[52:53]
	v_exp_f32_e32 v88, v88
	v_exp_f32_e32 v89, v89
	v_exp_f32_e32 v90, v90
	v_exp_f32_e32 v91, v91
	v_exp_f32_e32 v92, v92
	v_exp_f32_e32 v93, v93
	global_load_dwordx4 v[224:227], v180, s[54:55] offset:256
	v_exp_f32_e32 v94, v94
	v_exp_f32_e32 v95, v95
	v_exp_f32_e32 v64, v64
	v_exp_f32_e32 v65, v65
	v_exp_f32_e32 v66, v66
	v_exp_f32_e32 v67, v67
	global_load_dwordx4 v[228:231], v180, s[56:57] offset:256
	v_exp_f32_e32 v68, v68
	v_exp_f32_e32 v69, v69
	v_exp_f32_e32 v70, v70
	v_exp_f32_e32 v71, v71
	v_exp_f32_e32 v72, v72
	v_exp_f32_e32 v73, v73
	global_load_dwordx4 v[240:243], v181, s[58:59]
	v_exp_f32_e32 v74, v74
	v_exp_f32_e32 v75, v75
	v_exp_f32_e32 v76, v76
	v_exp_f32_e32 v77, v77
	v_exp_f32_e32 v78, v78
	v_exp_f32_e32 v79, v79
	v_add_f32_e32 v249, v80, v81
	v_add_f32_e32 v250, v82, v83
	v_add_f32_e32 v251, v84, v85
	v_add_f32_e32 v182, v86, v87
	v_add_f32_e32 v249, v88, v249
	v_add_f32_e32 v250, v89, v250
	v_add_f32_e32 v251, v90, v251
	v_add_f32_e32 v182, v91, v182
	v_add_f32_e32 v249, v92, v249
	v_add_f32_e32 v250, v93, v250
	v_add_f32_e32 v251, v94, v251
	v_add_f32_e32 v182, v95, v182
	v_add_f32_e32 v249, v64, v249
	v_add_f32_e32 v250, v65, v250
	v_add_f32_e32 v251, v66, v251
	v_add_f32_e32 v182, v67, v182
	v_add_f32_e32 v249, v68, v249
	v_add_f32_e32 v250, v69, v250
	v_add_f32_e32 v251, v70, v251
	v_add_f32_e32 v182, v71, v182
	v_add_f32_e32 v249, v72, v249
	v_add_f32_e32 v250, v73, v250
	v_add_f32_e32 v251, v74, v251
	v_add_f32_e32 v182, v75, v182
	v_add_f32_e32 v249, v76, v249
	v_add_f32_e32 v250, v77, v250
	v_add_f32_e32 v251, v78, v251
	v_add_f32_e32 v182, v79, v182
	v_add_f32_e32 v249, v249, v250
	v_add_f32_e32 v251, v251, v182
	v_add_f32_e32 v249, v249, v251
	v_add_f32_e32 v176, v176, v249
	v_cvt_pk_bf16_f32 v144, v80, v81
	v_cvt_pk_bf16_f32 v145, v82, v83
	v_cvt_pk_bf16_f32 v146, v84, v85
	v_cvt_pk_bf16_f32 v147, v86, v87
	v_cvt_pk_bf16_f32 v148, v88, v89
	v_cvt_pk_bf16_f32 v149, v90, v91
	v_cvt_pk_bf16_f32 v150, v92, v93
	v_cvt_pk_bf16_f32 v151, v94, v95
	v_cvt_pk_bf16_f32 v152, v64, v65
	v_cvt_pk_bf16_f32 v153, v66, v67
	v_cvt_pk_bf16_f32 v154, v68, v69
	v_cvt_pk_bf16_f32 v155, v70, v71
	v_cvt_pk_bf16_f32 v156, v72, v73
	v_cvt_pk_bf16_f32 v157, v74, v75
	v_cvt_pk_bf16_f32 v158, v76, v77
	v_cvt_pk_bf16_f32 v159, v78, v79

; __device__ __forceinline__ void partialSM(f32x16& p0, f32x16& p1, float& m_reg, float& mn, float& alpha) {
;   constexpr float C = SCALE * 1.4426950408889634f;
;   float pmax = p0[0]; for (int r = 1; r < 16; ++r) pmax = fmaxf(pmax, p0[r]); for (int r = 0; r < 16; ++r) pmax = fmaxf(pmax, p1[r]);
;   { auto rr = __builtin_amdgcn_permlane32_swap(__float_as_uint(pmax), __float_as_uint(pmax), false, false);
;     pmax = fmaxf(__uint_as_float(rr[0]), __uint_as_float(rr[1])); }
;   if (__builtin_expect(__all(pmax - m_reg <= THR / SCALE), 1)) { mn = m_reg; alpha = 1.f; }
;   else { mn = fmaxf(m_reg, pmax); alpha = __builtin_amdgcn_exp2f((m_reg - mn) * C); m_reg = mn; }
;   float mnC = -mn * C;
;   for (int r = 0; r < 16; ++r) p0[r] = fmaf(p0[r], C, mnC); for (int r = 0; r < 16; ++r) p1[r] = fmaf(p1[r], C, mnC);
;   for (int r = 0; r < 16; ++r) p0[r] = __builtin_amdgcn_exp2f(p0[r]);
; }
.Lpp_safe_Ba:
	global_load_dwordx4 v[232:235], v180, s[50:51]
	global_load_dwordx4 v[236:239], v180, s[52:53]
	global_load_dwordx4 v[224:227], v180, s[54:55] offset:256
	global_load_dwordx4 v[228:231], v180, s[56:57] offset:256
	global_load_dwordx4 v[240:243], v181, s[58:59]
	v_mov_b32_e32 v251, v250
	s_nop 1
	v_permlane32_swap_b32_e32 v250, v251
	v_max_f32_e32 v250, v250, v251
	v_sub_f32_e32 v251, v250, v175
	v_cmp_ge_f32_e32 vcc, 0x4138aa3b, v251
	v_max_f32_e32 v249, v175, v250
	v_sub_f32_e32 v251, v175, v249
	v_exp_f32_e32 v251, v251
	s_nop 1
	s_cmp_eq_u64 vcc, exec
	s_cselect_b64 s[8:9], -1, 0
	v_cndmask_b32_e64 v177, v251, 1.0, s[8:9]
	v_cndmask_b32_e64 v175, v249, v175, s[8:9]
	v_cmp_gt_f32_e32 vcc, 1.0, v177
	s_nop 4
	s_cbranch_vccz .Lpp_nr_Ba
	s_and_saveexec_b64 s[42:43], s[6:7]
	ds_write_b32 v186, v177 offset:128
	s_or_b64 exec, exec, s[42:43]
	s_waitcnt lgkmcnt(0)
	v_add_u32_e32 v187, v179, v172
	ds_read_b128 v[192:195], v187 offset:128
	ds_read_b128 v[196:199], v187 offset:160
	ds_read_b128 v[200:203], v187 offset:192
	ds_read_b128 v[204:207], v187 offset:224
	s_waitcnt lgkmcnt(0)
	v_pk_mul_f32 v[0:1], v[0:1], v[192:193]
	v_pk_mul_f32 v[2:3], v[2:3], v[194:195]
	v_pk_mul_f32 v[4:5], v[4:5], v[196:197]
	v_pk_mul_f32 v[6:7], v[6:7], v[198:199]
	v_pk_mul_f32 v[8:9], v[8:9], v[200:201]
	v_pk_mul_f32 v[10:11], v[10:11], v[202:203]
	v_pk_mul_f32 v[12:13], v[12:13], v[204:205]
	v_pk_mul_f32 v[14:15], v[14:15], v[206:207]
	v_pk_mul_f32 v[48:49], v[48:49], v[192:193]
	v_pk_mul_f32 v[50:51], v[50:51], v[194:195]
	v_pk_mul_f32 v[52:53], v[52:53], v[196:197]
	v_pk_mul_f32 v[54:55], v[54:55], v[198:199]
	v_pk_mul_f32 v[56:57], v[56:57], v[200:201]
	v_pk_mul_f32 v[58:59], v[58:59], v[202:203]
	v_pk_mul_f32 v[60:61], v[60:61], v[204:205]
	v_pk_mul_f32 v[62:63], v[62:63], v[206:207]
	v_pk_mul_f32 v[32:33], v[32:33], v[192:193]
	v_pk_mul_f32 v[34:35], v[34:35], v[194:195]
	v_pk_mul_f32 v[36:37], v[36:37], v[196:197]
	v_pk_mul_f32 v[38:39], v[38:39], v[198:199]
	v_pk_mul_f32 v[40:41], v[40:41], v[200:201]
	v_pk_mul_f32 v[42:43], v[42:43], v[202:203]
	v_pk_mul_f32 v[44:45], v[44:45], v[204:205]
	v_pk_mul_f32 v[46:47], v[46:47], v[206:207]
	v_pk_mul_f32 v[16:17], v[16:17], v[192:193]
	v_pk_mul_f32 v[18:19], v[18:19], v[194:195]
	v_pk_mul_f32 v[20:21], v[20:21], v[196:197]
	v_pk_mul_f32 v[22:23], v[22:23], v[198:199]
	v_pk_mul_f32 v[24:25], v[24:25], v[200:201]
	v_pk_mul_f32 v[26:27], v[26:27], v[202:203]
	v_pk_mul_f32 v[28:29], v[28:29], v[204:205]
	v_pk_mul_f32 v[30:31], v[30:31], v[206:207]
	s_nop 1
	ds_read_b128 v[192:195], v160 offset:16384
	ds_read_b128 v[196:199], v160 offset:24576
	ds_read_b128 v[200:203], v161 offset:16384
	ds_read_b128 v[204:207], v161 offset:24576
	s_waitcnt lgkmcnt(0)

; __device__ __forceinline__ void partialSM(f32x16& p0, f32x16& p1, float& m_reg, float& mn, float& alpha) {
;   constexpr float C = SCALE * 1.4426950408889634f;
;   float pmax = p0[0]; for (int r = 1; r < 16; ++r) pmax = fmaxf(pmax, p0[r]); for (int r = 0; r < 16; ++r) pmax = fmaxf(pmax, p1[r]);
;   { auto rr = __builtin_amdgcn_permlane32_swap(__float_as_uint(pmax), __float_as_uint(pmax), false, false);
;     pmax = fmaxf(__uint_as_float(rr[0]), __uint_as_float(rr[1])); }
;   if (__builtin_expect(__all(pmax - m_reg <= THR / SCALE), 1)) { mn = m_reg; alpha = 1.f; }
;   else { mn = fmaxf(m_reg, pmax); alpha = __builtin_amdgcn_exp2f((m_reg - mn) * C); m_reg = mn; }
;   float mnC = -mn * C;
;   for (int r = 0; r < 16; ++r) p0[r] = fmaf(p0[r], C, mnC); for (int r = 0; r < 16; ++r) p1[r] = fmaf(p1[r], C, mnC);
;   for (int r = 0; r < 16; ++r) p0[r] = __builtin_amdgcn_exp2f(p0[r]);
; }
.Lpp_safe_Bb:
	global_load_dwordx4 v[232:235], v180, s[50:51]
	global_load_dwordx4 v[236:239], v180, s[52:53]
	global_load_dwordx4 v[224:227], v180, s[54:55] offset:256
	global_load_dwordx4 v[228:231], v180, s[56:57] offset:256
	global_load_dwordx4 v[240:243], v181, s[58:59]
	v_mov_b32_e32 v251, v250
	s_nop 1
	v_permlane32_swap_b32_e32 v250, v251
	v_max_f32_e32 v250, v250, v251
	v_sub_f32_e32 v251, v250, v175
	v_cmp_ge_f32_e32 vcc, 0x4138aa3b, v251
	v_max_f32_e32 v249, v175, v250
	v_sub_f32_e32 v251, v175, v249
	v_exp_f32_e32 v251, v251
	s_nop 1
	s_cmp_eq_u64 vcc, exec
	s_cselect_b64 s[8:9], -1, 0
	v_cndmask_b32_e64 v177, v251, 1.0, s[8:9]
	v_cndmask_b32_e64 v175, v249, v175, s[8:9]
	v_cmp_gt_f32_e32 vcc, 1.0, v177
	s_nop 4
	s_cbranch_vccz .Lpp_nr_Bb
	s_and_saveexec_b64 s[42:43], s[6:7]
	ds_write_b32 v186, v177 offset:128
	s_or_b64 exec, exec, s[42:43]
	s_waitcnt lgkmcnt(0)
	v_add_u32_e32 v187, v179, v172
	ds_read_b128 v[192:195], v187 offset:128
	ds_read_b128 v[196:199], v187 offset:160
	ds_read_b128 v[200:203], v187 offset:192
	ds_read_b128 v[204:207], v187 offset:224
	s_waitcnt lgkmcnt(0)
	v_pk_mul_f32 v[0:1], v[0:1], v[192:193]
	v_pk_mul_f32 v[2:3], v[2:3], v[194:195]
	v_pk_mul_f32 v[4:5], v[4:5], v[196:197]
	v_pk_mul_f32 v[6:7], v[6:7], v[198:199]
	v_pk_mul_f32 v[8:9], v[8:9], v[200:201]
	v_pk_mul_f32 v[10:11], v[10:11], v[202:203]
	v_pk_mul_f32 v[12:13], v[12:13], v[204:205]
	v_pk_mul_f32 v[14:15], v[14:15], v[206:207]
	v_pk_mul_f32 v[48:49], v[48:49], v[192:193]
	v_pk_mul_f32 v[50:51], v[50:51], v[194:195]
	v_pk_mul_f32 v[52:53], v[52:53], v[196:197]
	v_pk_mul_f32 v[54:55], v[54:55], v[198:199]
	v_pk_mul_f32 v[56:57], v[56:57], v[200:201]
	v_pk_mul_f32 v[58:59], v[58:59], v[202:203]
	v_pk_mul_f32 v[60:61], v[60:61], v[204:205]
	v_pk_mul_f32 v[62:63], v[62:63], v[206:207]
	v_pk_mul_f32 v[32:33], v[32:33], v[192:193]
	v_pk_mul_f32 v[34:35], v[34:35], v[194:195]
	v_pk_mul_f32 v[36:37], v[36:37], v[196:197]
	v_pk_mul_f32 v[38:39], v[38:39], v[198:199]
	v_pk_mul_f32 v[40:41], v[40:41], v[200:201]
	v_pk_mul_f32 v[42:43], v[42:43], v[202:203]
	v_pk_mul_f32 v[44:45], v[44:45], v[204:205]
	v_pk_mul_f32 v[46:47], v[46:47], v[206:207]
	v_pk_mul_f32 v[16:17], v[16:17], v[192:193]
	v_pk_mul_f32 v[18:19], v[18:19], v[194:195]
	v_pk_mul_f32 v[20:21], v[20:21], v[196:197]
	v_pk_mul_f32 v[22:23], v[22:23], v[198:199]
	v_pk_mul_f32 v[24:25], v[24:25], v[200:201]
	v_pk_mul_f32 v[26:27], v[26:27], v[202:203]
	v_pk_mul_f32 v[28:29], v[28:29], v[204:205]
	v_pk_mul_f32 v[30:31], v[30:31], v[206:207]
	s_nop 1
	ds_read_b128 v[192:195], v160
	ds_read_b128 v[196:199], v160 offset:8192
	ds_read_b128 v[200:203], v161
	ds_read_b128 v[204:207], v161 offset:8192
	s_waitcnt lgkmcnt(0)

; __device__ __forceinline__ void partialSM(f32x16& p0, f32x16& p1, float& m_reg, float& mn, float& alpha) {
;   constexpr float C = SCALE * 1.4426950408889634f;
;   float pmax = p0[0]; for (int r = 1; r < 16; ++r) pmax = fmaxf(pmax, p0[r]); for (int r = 0; r < 16; ++r) pmax = fmaxf(pmax, p1[r]);
;   { auto rr = __builtin_amdgcn_permlane32_swap(__float_as_uint(pmax), __float_as_uint(pmax), false, false);
;     pmax = fmaxf(__uint_as_float(rr[0]), __uint_as_float(rr[1])); }
;   if (__builtin_expect(__all(pmax - m_reg <= THR / SCALE), 1)) { mn = m_reg; alpha = 1.f; }
;   else { mn = fmaxf(m_reg, pmax); alpha = __builtin_amdgcn_exp2f((m_reg - mn) * C); m_reg = mn; }
;   float mnC = -mn * C;
;   for (int r = 0; r < 16; ++r) p0[r] = fmaf(p0[r], C, mnC); for (int r = 0; r < 16; ++r) p1[r] = fmaf(p1[r], C, mnC);
;   for (int r = 0; r < 16; ++r) p0[r] = __builtin_amdgcn_exp2f(p0[r]);
; }
.Lpp_safe_Aa:
	global_load_dwordx4 v[232:235], v180, s[50:51]
	global_load_dwordx4 v[236:239], v180, s[52:53]
	global_load_dwordx4 v[224:227], v180, s[54:55] offset:256
	global_load_dwordx4 v[228:231], v180, s[56:57] offset:256
	global_load_dwordx4 v[240:243], v181, s[58:59]
	v_mov_b32_e32 v251, v250
	s_nop 1
	v_permlane32_swap_b32_e32 v250, v251
	v_max_f32_e32 v250, v250, v251
	v_sub_f32_e32 v251, v250, v175
	v_cmp_ge_f32_e32 vcc, 0x4138aa3b, v251
	v_max_f32_e32 v249, v175, v250
	v_sub_f32_e32 v251, v175, v249
	v_exp_f32_e32 v251, v251
	s_nop 1
	s_cmp_eq_u64 vcc, exec
	s_cselect_b64 s[8:9], -1, 0
	v_cndmask_b32_e64 v177, v251, 1.0, s[8:9]
	v_cndmask_b32_e64 v175, v249, v175, s[8:9]
	v_cmp_gt_f32_e32 vcc, 1.0, v177
	s_nop 4
	s_cbranch_vccz .Lpp_nr_Aa
	s_and_saveexec_b64 s[42:43], s[6:7]
	ds_write_b32 v186, v177 offset:128
	s_or_b64 exec, exec, s[42:43]
	s_waitcnt lgkmcnt(0)
	v_add_u32_e32 v187, v179, v172
	ds_read_b128 v[192:195], v187 offset:128
	ds_read_b128 v[196:199], v187 offset:160
	ds_read_b128 v[200:203], v187 offset:192
	ds_read_b128 v[204:207], v187 offset:224
	s_waitcnt lgkmcnt(0)
	v_pk_mul_f32 v[0:1], v[0:1], v[192:193]
	v_pk_mul_f32 v[2:3], v[2:3], v[194:195]
	v_pk_mul_f32 v[4:5], v[4:5], v[196:197]
	v_pk_mul_f32 v[6:7], v[6:7], v[198:199]
	v_pk_mul_f32 v[8:9], v[8:9], v[200:201]
	v_pk_mul_f32 v[10:11], v[10:11], v[202:203]
	v_pk_mul_f32 v[12:13], v[12:13], v[204:205]
	v_pk_mul_f32 v[14:15], v[14:15], v[206:207]
	v_pk_mul_f32 v[48:49], v[48:49], v[192:193]
	v_pk_mul_f32 v[50:51], v[50:51], v[194:195]
	v_pk_mul_f32 v[52:53], v[52:53], v[196:197]
	v_pk_mul_f32 v[54:55], v[54:55], v[198:199]
	v_pk_mul_f32 v[56:57], v[56:57], v[200:201]
	v_pk_mul_f32 v[58:59], v[58:59], v[202:203]
	v_pk_mul_f32 v[60:61], v[60:61], v[204:205]
	v_pk_mul_f32 v[62:63], v[62:63], v[206:207]
	v_pk_mul_f32 v[32:33], v[32:33], v[192:193]
	v_pk_mul_f32 v[34:35], v[34:35], v[194:195]
	v_pk_mul_f32 v[36:37], v[36:37], v[196:197]
	v_pk_mul_f32 v[38:39], v[38:39], v[198:199]
	v_pk_mul_f32 v[40:41], v[40:41], v[200:201]
	v_pk_mul_f32 v[42:43], v[42:43], v[202:203]
	v_pk_mul_f32 v[44:45], v[44:45], v[204:205]
	v_pk_mul_f32 v[46:47], v[46:47], v[206:207]
	v_pk_mul_f32 v[16:17], v[16:17], v[192:193]
	v_pk_mul_f32 v[18:19], v[18:19], v[194:195]
	v_pk_mul_f32 v[20:21], v[20:21], v[196:197]
	v_pk_mul_f32 v[22:23], v[22:23], v[198:199]
	v_pk_mul_f32 v[24:25], v[24:25], v[200:201]
	v_pk_mul_f32 v[26:27], v[26:27], v[202:203]
	v_pk_mul_f32 v[28:29], v[28:29], v[204:205]
	v_pk_mul_f32 v[30:31], v[30:31], v[206:207]
